# XCD barrier: non-leader workgroups poll the global generation word directly instead of the per-XCD word
# speedup vs baseline: 1.0141x; 1.0004x over previous
.LBB0_169:
	s_or_b64 exec, exec, s[6:7]
	v_cvt_f32_u32_e32 v4, v2
	s_waitcnt vmcnt(0)
	v_readfirstlane_b32 s4, v3
	v_sub_u32_e32 v3, 0, v2
	v_rcp_iflag_f32_e32 v4, v4
	v_add_u32_e32 v5, s4, v1
	v_mul_f32_e32 v4, 0x4f7ffffe, v4
	v_cvt_u32_f32_e32 v4, v4
	v_mul_lo_u32 v1, v3, v4
	v_mul_hi_u32 v1, v4, v1
	v_add_u32_e32 v1, v4, v1
	v_mul_hi_u32 v1, v5, v1
	v_mul_lo_u32 v3, v1, v2
	v_sub_u32_e32 v3, v5, v3
	v_add_u32_e32 v4, 1, v1
	v_cmp_ge_u32_e32 vcc, v3, v2
	s_nop 1
	v_cndmask_b32_e32 v1, v1, v4, vcc
	v_sub_u32_e32 v4, v3, v2
	v_cndmask_b32_e32 v3, v3, v4, vcc
	v_add_u32_e32 v4, 1, v1
	v_cmp_ge_u32_e32 vcc, v3, v2
	v_add_u32_e32 v3, 1, v5
	s_nop 0
	v_cndmask_b32_e32 v1, v1, v4, vcc
	v_mul_lo_u32 v4, v2, v1
	v_add_u32_e32 v2, v4, v2
	v_cmp_ne_u32_e32 vcc, v3, v2
	s_and_saveexec_b64 s[4:5], vcc
	s_xor_b64 s[4:5], exec, s[4:5]
	s_cbranch_execz .LBB0_183
	s_waitcnt lgkmcnt(0)
	v_mov_b32_e32 v0, 0
	s_add_u32 s10, s64, 0x2f97500
	s_addc_u32 s11, s65, 0
	global_load_dword v0, v0, s[10:11] sc1
	s_waitcnt vmcnt(0)
	v_cmp_eq_u32_e32 vcc, v0, v1
	s_and_saveexec_b64 s[6:7], vcc
	s_cbranch_execz .LBB0_182
	s_add_u32 s8, s64, 0x2f94200
	s_addc_u32 s9, s65, 0
	s_mov_b32 s24, 1
	s_mov_b64 s[12:13], 0
	v_mov_b32_e32 v0, 0
	s_branch .LBB0_173

.LBB0_441:
	s_or_b64 exec, exec, s[6:7]
	v_cvt_f32_u32_e32 v4, v2
	s_waitcnt vmcnt(0)
	v_readfirstlane_b32 s4, v3
	v_sub_u32_e32 v3, 0, v2
	v_rcp_iflag_f32_e32 v4, v4
	v_add_u32_e32 v5, s4, v1
	v_mul_f32_e32 v4, 0x4f7ffffe, v4
	v_cvt_u32_f32_e32 v4, v4
	v_mul_lo_u32 v1, v3, v4
	v_mul_hi_u32 v1, v4, v1
	v_add_u32_e32 v1, v4, v1
	v_mul_hi_u32 v1, v5, v1
	v_mul_lo_u32 v3, v1, v2
	v_sub_u32_e32 v3, v5, v3
	v_add_u32_e32 v4, 1, v1
	v_cmp_ge_u32_e32 vcc, v3, v2
	s_nop 1
	v_cndmask_b32_e32 v1, v1, v4, vcc
	v_sub_u32_e32 v4, v3, v2
	v_cndmask_b32_e32 v3, v3, v4, vcc
	v_add_u32_e32 v4, 1, v1
	v_cmp_ge_u32_e32 vcc, v3, v2
	v_add_u32_e32 v3, 1, v5
	s_nop 0
	v_cndmask_b32_e32 v1, v1, v4, vcc
	v_mul_lo_u32 v4, v2, v1
	v_add_u32_e32 v2, v4, v2
	v_cmp_ne_u32_e32 vcc, v3, v2
	s_and_saveexec_b64 s[4:5], vcc
	s_xor_b64 s[4:5], exec, s[4:5]
	s_cbranch_execz .LBB0_455
	s_waitcnt lgkmcnt(0)
	v_mov_b32_e32 v0, 0
	s_add_u32 s12, s64, 0x2f97500
	s_addc_u32 s13, s65, 0
	global_load_dword v0, v0, s[12:13] sc1
	s_waitcnt vmcnt(0)
	v_cmp_eq_u32_e32 vcc, v0, v1
	s_and_saveexec_b64 s[6:7], vcc
	s_cbranch_execz .LBB0_454
	s_add_u32 s10, s64, 0x2f94200
	s_addc_u32 s11, s65, 0
	s_mov_b32 s24, 1
	s_mov_b64 s[14:15], 0
	v_mov_b32_e32 v0, 0
	s_branch .LBB0_445

.LBB0_651:
	s_or_b64 exec, exec, s[6:7]
	v_cvt_f32_u32_e32 v4, v2
	s_waitcnt vmcnt(0)
	v_readfirstlane_b32 s4, v3
	v_sub_u32_e32 v3, 0, v2
	v_rcp_iflag_f32_e32 v4, v4
	v_add_u32_e32 v5, s4, v1
	v_mul_f32_e32 v4, 0x4f7ffffe, v4
	v_cvt_u32_f32_e32 v4, v4
	v_mul_lo_u32 v1, v3, v4
	v_mul_hi_u32 v1, v4, v1
	v_add_u32_e32 v1, v4, v1
	v_mul_hi_u32 v1, v5, v1
	v_mul_lo_u32 v3, v1, v2
	v_sub_u32_e32 v3, v5, v3
	v_add_u32_e32 v4, 1, v1
	v_cmp_ge_u32_e32 vcc, v3, v2
	s_nop 1
	v_cndmask_b32_e32 v1, v1, v4, vcc
	v_sub_u32_e32 v4, v3, v2
	v_cndmask_b32_e32 v3, v3, v4, vcc
	v_add_u32_e32 v4, 1, v1
	v_cmp_ge_u32_e32 vcc, v3, v2
	v_add_u32_e32 v3, 1, v5
	s_nop 0
	v_cndmask_b32_e32 v1, v1, v4, vcc
	v_mul_lo_u32 v4, v2, v1
	v_add_u32_e32 v2, v4, v2
	v_cmp_ne_u32_e32 vcc, v3, v2
	s_and_saveexec_b64 s[4:5], vcc
	s_xor_b64 s[4:5], exec, s[4:5]
	s_cbranch_execz .LBB0_665
	s_waitcnt lgkmcnt(0)
	v_mov_b32_e32 v0, 0
	s_add_u32 s18, s64, 0x2f97500
	s_addc_u32 s19, s65, 0
	global_load_dword v0, v0, s[18:19] sc1
	s_waitcnt vmcnt(0)
	v_cmp_eq_u32_e32 vcc, v0, v1
	s_and_saveexec_b64 s[6:7], vcc
	s_cbranch_execz .LBB0_664
	s_add_u32 s16, s64, 0x2f94200
	s_addc_u32 s17, s65, 0
	s_mov_b32 s30, 1
	s_mov_b64 s[20:21], 0
	v_mov_b32_e32 v0, 0
	s_branch .LBB0_655

.LBB0_739:
	s_or_b64 exec, exec, s[14:15]
	v_cvt_f32_u32_e32 v4, v2
	s_waitcnt vmcnt(0)
	v_readfirstlane_b32 s6, v3
	v_sub_u32_e32 v3, 0, v2
	v_rcp_iflag_f32_e32 v4, v4
	v_add_u32_e32 v5, s6, v1
	v_mul_f32_e32 v4, 0x4f7ffffe, v4
	v_cvt_u32_f32_e32 v4, v4
	v_mul_lo_u32 v1, v3, v4
	v_mul_hi_u32 v1, v4, v1
	v_add_u32_e32 v1, v4, v1
	v_mul_hi_u32 v1, v5, v1
	v_mul_lo_u32 v3, v1, v2
	v_sub_u32_e32 v3, v5, v3
	v_add_u32_e32 v4, 1, v1
	v_cmp_ge_u32_e32 vcc, v3, v2
	s_nop 1
	v_cndmask_b32_e32 v1, v1, v4, vcc
	v_sub_u32_e32 v4, v3, v2
	v_cndmask_b32_e32 v3, v3, v4, vcc
	v_add_u32_e32 v4, 1, v1
	v_cmp_ge_u32_e32 vcc, v3, v2
	v_add_u32_e32 v3, 1, v5
	s_nop 0
	v_cndmask_b32_e32 v1, v1, v4, vcc
	v_mul_lo_u32 v4, v2, v1
	v_add_u32_e32 v2, v4, v2
	v_cmp_ne_u32_e32 vcc, v3, v2
	s_and_saveexec_b64 s[6:7], vcc
	s_xor_b64 s[6:7], exec, s[6:7]
	s_cbranch_execz .LBB0_753
	s_waitcnt lgkmcnt(0)
	v_mov_b32_e32 v0, 0
	s_add_u32 s18, s64, 0x2f97500
	s_addc_u32 s19, s65, 0
	global_load_dword v0, v0, s[18:19] sc1
	s_waitcnt vmcnt(0)
	v_cmp_eq_u32_e32 vcc, v0, v1
	s_and_saveexec_b64 s[14:15], vcc
	s_cbranch_execz .LBB0_752
	s_add_u32 s16, s64, 0x2f94200
	s_addc_u32 s17, s65, 0
	s_mov_b32 s30, 1
	s_mov_b64 s[20:21], 0
	v_mov_b32_e32 v0, 0
	s_branch .LBB0_743

.LBB0_813:
	s_or_b64 exec, exec, s[6:7]
	v_cvt_f32_u32_e32 v4, v2
	s_waitcnt vmcnt(0)
	v_readfirstlane_b32 s4, v3
	v_sub_u32_e32 v3, 0, v2
	v_rcp_iflag_f32_e32 v4, v4
	v_add_u32_e32 v5, s4, v1
	v_mul_f32_e32 v4, 0x4f7ffffe, v4
	v_cvt_u32_f32_e32 v4, v4
	v_mul_lo_u32 v1, v3, v4
	v_mul_hi_u32 v1, v4, v1
	v_add_u32_e32 v1, v4, v1
	v_mul_hi_u32 v1, v5, v1
	v_mul_lo_u32 v3, v1, v2
	v_sub_u32_e32 v3, v5, v3
	v_add_u32_e32 v4, 1, v1
	v_cmp_ge_u32_e32 vcc, v3, v2
	s_nop 1
	v_cndmask_b32_e32 v1, v1, v4, vcc
	v_sub_u32_e32 v4, v3, v2
	v_cndmask_b32_e32 v3, v3, v4, vcc
	v_add_u32_e32 v4, 1, v1
	v_cmp_ge_u32_e32 vcc, v3, v2
	v_add_u32_e32 v3, 1, v5
	s_nop 0
	v_cndmask_b32_e32 v1, v1, v4, vcc
	v_mul_lo_u32 v4, v2, v1
	v_add_u32_e32 v2, v4, v2
	v_cmp_ne_u32_e32 vcc, v3, v2
	s_and_saveexec_b64 s[4:5], vcc
	s_xor_b64 s[4:5], exec, s[4:5]
	s_cbranch_execz .LBB0_827
	s_waitcnt lgkmcnt(0)
	v_mov_b32_e32 v0, 0
	s_add_u32 s16, s64, 0x2f97500
	s_addc_u32 s17, s65, 0
	global_load_dword v0, v0, s[16:17] sc1
	s_waitcnt vmcnt(0)
	v_cmp_eq_u32_e32 vcc, v0, v1
	s_and_saveexec_b64 s[6:7], vcc
	s_cbranch_execz .LBB0_826
	s_add_u32 s14, s64, 0x2f94200
	s_addc_u32 s15, s65, 0
	s_mov_b32 s28, 1
	s_mov_b64 s[18:19], 0
	v_mov_b32_e32 v0, 0
	s_branch .LBB0_817

.LBB0_930:
	s_or_b64 exec, exec, s[6:7]
	v_cvt_f32_u32_e32 v4, v2
	s_waitcnt vmcnt(0)
	v_readfirstlane_b32 s4, v3
	v_sub_u32_e32 v3, 0, v2
	v_rcp_iflag_f32_e32 v4, v4
	v_add_u32_e32 v5, s4, v1
	v_mul_f32_e32 v4, 0x4f7ffffe, v4
	v_cvt_u32_f32_e32 v4, v4
	v_mul_lo_u32 v1, v3, v4
	v_mul_hi_u32 v1, v4, v1
	v_add_u32_e32 v1, v4, v1
	v_mul_hi_u32 v1, v5, v1
	v_mul_lo_u32 v3, v1, v2
	v_sub_u32_e32 v3, v5, v3
	v_add_u32_e32 v4, 1, v1
	v_cmp_ge_u32_e32 vcc, v3, v2
	s_nop 1
	v_cndmask_b32_e32 v1, v1, v4, vcc
	v_sub_u32_e32 v4, v3, v2
	v_cndmask_b32_e32 v3, v3, v4, vcc
	v_add_u32_e32 v4, 1, v1
	v_cmp_ge_u32_e32 vcc, v3, v2
	v_add_u32_e32 v3, 1, v5
	s_nop 0
	v_cndmask_b32_e32 v1, v1, v4, vcc
	v_mul_lo_u32 v4, v2, v1
	v_add_u32_e32 v2, v4, v2
	v_cmp_ne_u32_e32 vcc, v3, v2
	s_and_saveexec_b64 s[4:5], vcc
	s_xor_b64 s[4:5], exec, s[4:5]
	s_cbranch_execz .LBB0_944
	s_waitcnt lgkmcnt(0)
	v_mov_b32_e32 v0, 0
	s_add_u32 s20, s64, 0x2f97500
	s_addc_u32 s21, s65, 0
	global_load_dword v0, v0, s[20:21] sc1
	s_waitcnt vmcnt(0)
	v_cmp_eq_u32_e32 vcc, v0, v1
	s_and_saveexec_b64 s[6:7], vcc
	s_cbranch_execz .LBB0_943
	s_add_u32 s18, s64, 0x2f94200
	s_addc_u32 s19, s65, 0
	s_mov_b32 s33, 1
	s_mov_b64 s[22:23], 0
	v_mov_b32_e32 v0, 0
	s_branch .LBB0_934

.LBB0_991:
	s_or_b64 exec, exec, s[10:11]
	v_cvt_f32_u32_e32 v4, v2
	s_waitcnt vmcnt(0)
	v_readfirstlane_b32 s6, v3
	v_sub_u32_e32 v3, 0, v2
	v_rcp_iflag_f32_e32 v4, v4
	v_add_u32_e32 v5, s6, v1
	v_mul_f32_e32 v4, 0x4f7ffffe, v4
	v_cvt_u32_f32_e32 v4, v4
	v_mul_lo_u32 v1, v3, v4
	v_mul_hi_u32 v1, v4, v1
	v_add_u32_e32 v1, v4, v1
	v_mul_hi_u32 v1, v5, v1
	v_mul_lo_u32 v3, v1, v2
	v_sub_u32_e32 v3, v5, v3
	v_add_u32_e32 v4, 1, v1
	v_cmp_ge_u32_e32 vcc, v3, v2
	s_nop 1
	v_cndmask_b32_e32 v1, v1, v4, vcc
	v_sub_u32_e32 v4, v3, v2
	v_cndmask_b32_e32 v3, v3, v4, vcc
	v_add_u32_e32 v4, 1, v1
	v_cmp_ge_u32_e32 vcc, v3, v2
	v_add_u32_e32 v3, 1, v5
	s_nop 0
	v_cndmask_b32_e32 v1, v1, v4, vcc
	v_mul_lo_u32 v4, v2, v1
	v_add_u32_e32 v2, v4, v2
	v_cmp_ne_u32_e32 vcc, v3, v2
	s_and_saveexec_b64 s[6:7], vcc
	s_xor_b64 s[6:7], exec, s[6:7]
	s_cbranch_execz .LBB0_1005
	s_waitcnt lgkmcnt(0)
	v_mov_b32_e32 v0, 0
	s_add_u32 s14, s64, 0x2f97500
	s_addc_u32 s15, s65, 0
	global_load_dword v0, v0, s[14:15] sc1
	s_waitcnt vmcnt(0)
	v_cmp_eq_u32_e32 vcc, v0, v1
	s_and_saveexec_b64 s[10:11], vcc
	s_cbranch_execz .LBB0_1004
	s_add_u32 s12, s64, 0x2f94200
	s_addc_u32 s13, s65, 0
	s_mov_b32 s26, 1
	s_mov_b64 s[16:17], 0
	v_mov_b32_e32 v0, 0
	s_branch .LBB0_995

.LBB0_1336:
	s_or_b64 exec, exec, s[12:13]
	v_cvt_f32_u32_e32 v4, v2
	s_waitcnt vmcnt(0)
	v_readfirstlane_b32 s4, v3
	v_sub_u32_e32 v3, 0, v2
	v_rcp_iflag_f32_e32 v4, v4
	v_add_u32_e32 v5, s4, v1
	v_mul_f32_e32 v4, 0x4f7ffffe, v4
	v_cvt_u32_f32_e32 v4, v4
	v_mul_lo_u32 v1, v3, v4
	v_mul_hi_u32 v1, v4, v1
	v_add_u32_e32 v1, v4, v1
	v_mul_hi_u32 v1, v5, v1
	v_mul_lo_u32 v3, v1, v2
	v_sub_u32_e32 v3, v5, v3
	v_add_u32_e32 v4, 1, v1
	v_cmp_ge_u32_e32 vcc, v3, v2
	s_nop 1
	v_cndmask_b32_e32 v1, v1, v4, vcc
	v_sub_u32_e32 v4, v3, v2
	v_cndmask_b32_e32 v3, v3, v4, vcc
	v_add_u32_e32 v4, 1, v1
	v_cmp_ge_u32_e32 vcc, v3, v2
	v_add_u32_e32 v3, 1, v5
	s_nop 0
	v_cndmask_b32_e32 v1, v1, v4, vcc
	v_mul_lo_u32 v4, v2, v1
	v_add_u32_e32 v2, v4, v2
	v_cmp_ne_u32_e32 vcc, v3, v2
	s_and_saveexec_b64 s[4:5], vcc
	s_xor_b64 s[4:5], exec, s[4:5]
	s_cbranch_execz .LBB0_1350
	s_waitcnt lgkmcnt(0)
	v_mov_b32_e32 v0, 0
	s_add_u32 s16, s64, 0x2f97500
	s_addc_u32 s17, s65, 0
	global_load_dword v0, v0, s[16:17] sc1
	s_waitcnt vmcnt(0)
	v_cmp_eq_u32_e32 vcc, v0, v1
	s_and_saveexec_b64 s[12:13], vcc
	s_cbranch_execz .LBB0_1349
	s_add_u32 s14, s64, 0x2f94200
	s_addc_u32 s15, s65, 0
	s_mov_b32 s28, 1
	s_mov_b64 s[18:19], 0
	v_mov_b32_e32 v0, 0
	s_branch .LBB0_1340

.LBB0_1392:
	s_or_b64 exec, exec, s[12:13]
	v_cvt_f32_u32_e32 v4, v2
	s_waitcnt vmcnt(0)
	v_readfirstlane_b32 s10, v3
	v_sub_u32_e32 v3, 0, v2
	v_rcp_iflag_f32_e32 v4, v4
	v_add_u32_e32 v5, s10, v1
	v_mul_f32_e32 v4, 0x4f7ffffe, v4
	v_cvt_u32_f32_e32 v4, v4
	v_mul_lo_u32 v1, v3, v4
	v_mul_hi_u32 v1, v4, v1
	v_add_u32_e32 v1, v4, v1
	v_mul_hi_u32 v1, v5, v1
	v_mul_lo_u32 v3, v1, v2
	v_sub_u32_e32 v3, v5, v3
	v_add_u32_e32 v4, 1, v1
	v_cmp_ge_u32_e32 vcc, v3, v2
	s_nop 1
	v_cndmask_b32_e32 v1, v1, v4, vcc
	v_sub_u32_e32 v4, v3, v2
	v_cndmask_b32_e32 v3, v3, v4, vcc
	v_add_u32_e32 v4, 1, v1
	v_cmp_ge_u32_e32 vcc, v3, v2
	v_add_u32_e32 v3, 1, v5
	s_nop 0
	v_cndmask_b32_e32 v1, v1, v4, vcc
	v_mul_lo_u32 v4, v2, v1
	v_add_u32_e32 v2, v4, v2
	v_cmp_ne_u32_e32 vcc, v3, v2
	s_and_saveexec_b64 s[10:11], vcc
	s_xor_b64 s[10:11], exec, s[10:11]
	s_cbranch_execz .LBB0_1406
	s_waitcnt lgkmcnt(0)
	v_mov_b32_e32 v0, 0
	s_add_u32 s16, s64, 0x2f97500
	s_addc_u32 s17, s65, 0
	global_load_dword v0, v0, s[16:17] sc1
	s_waitcnt vmcnt(0)
	v_cmp_eq_u32_e32 vcc, v0, v1
	s_and_saveexec_b64 s[12:13], vcc
	s_cbranch_execz .LBB0_1405
	s_add_u32 s14, s64, 0x2f94200
	s_addc_u32 s15, s65, 0
	s_mov_b32 s28, 1
	s_mov_b64 s[18:19], 0
	v_mov_b32_e32 v0, 0
	s_branch .LBB0_1396
